# write-through (sc1) only for the last-round epilogue stores: HB (P1a) and mixer-B MIX (P1b)
# speedup vs baseline: 1.1003x; 1.1003x over previous
.LBB0_185:
	v_lshl_add_u32 v154, s86, 8, v139
	v_ashrrev_i32_e32 v155, 31, v154
	v_lshl_add_u32 v136, s11, 7, v157
	v_lshlrev_b64 v[152:153], 11, v[154:155]
	v_lshl_add_u64 v[152:153], s[50:51], 0, v[152:153]
	v_lshlrev_b64 v[166:167], 1, v[136:137]
	v_pk_mul_f32 v[162:163], v[124:125], v[116:117]
	v_lshl_add_u64 v[152:153], v[152:153], 0, v[166:167]
	v_pk_mul_f32 v[164:165], v[126:127], v[118:119]
	v_cvt_pk_bf16_f32 v162, v162, v163
	v_pk_mul_f32 v[168:169], v[122:123], v[114:115]
	v_pk_mul_f32 v[170:171], v[120:121], v[112:113]
	v_cvt_pk_bf16_f32 v163, v164, v165
	v_pk_mul_f32 v[172:173], v[104:105], v[96:97]
	v_cvt_pk_bf16_f32 v164, v170, v171
	v_cvt_pk_bf16_f32 v165, v168, v169
	global_store_dwordx4 v[152:153], v[162:165], off sc1
	v_pk_mul_f32 v[170:171], v[106:107], v[98:99]
	s_mov_b32 s0, 0x40000
	v_or_b32_e32 v162, 16, v154
	v_ashrrev_i32_e32 v163, 31, v162
	v_lshlrev_b64 v[162:163], 11, v[162:163]
	v_lshl_add_u64 v[162:163], s[50:51], 0, v[162:163]
	v_lshl_add_u64 v[168:169], v[162:163], 0, v[166:167]
	v_pk_mul_f32 v[162:163], v[108:109], v[100:101]
	v_pk_mul_f32 v[164:165], v[110:111], v[102:103]
	v_cvt_pk_bf16_f32 v162, v162, v163
	s_nop 0
	v_cvt_pk_bf16_f32 v163, v164, v165
	v_cvt_pk_bf16_f32 v164, v172, v173
	v_cvt_pk_bf16_f32 v165, v170, v171
	global_store_dwordx4 v[168:169], v[162:165], off sc1
	v_pk_mul_f32 v[170:171], v[90:91], v[82:83]
	v_pk_mul_f32 v[172:173], v[88:89], v[80:81]
	v_or_b32_e32 v162, 32, v154
	v_ashrrev_i32_e32 v163, 31, v162
	v_lshlrev_b64 v[162:163], 11, v[162:163]
	v_lshl_add_u64 v[162:163], s[50:51], 0, v[162:163]
	v_or_b32_e32 v154, 48, v154
	v_lshl_add_u64 v[168:169], v[162:163], 0, v[166:167]
	v_pk_mul_f32 v[162:163], v[92:93], v[84:85]
	v_ashrrev_i32_e32 v155, 31, v154
	v_pk_mul_f32 v[164:165], v[94:95], v[86:87]
	v_cvt_pk_bf16_f32 v162, v162, v163
	v_lshlrev_b64 v[154:155], 11, v[154:155]
	v_cvt_pk_bf16_f32 v163, v164, v165
	v_cvt_pk_bf16_f32 v164, v172, v173
	v_cvt_pk_bf16_f32 v165, v170, v171
	global_store_dwordx4 v[168:169], v[162:165], off sc1
	v_lshl_add_u64 v[154:155], s[50:51], 0, v[154:155]
	v_lshl_add_u64 v[154:155], v[154:155], 0, v[166:167]
	v_pk_mul_f32 v[162:163], v[76:77], v[68:69]
	v_pk_mul_f32 v[164:165], v[78:79], v[70:71]
	v_cvt_pk_bf16_f32 v162, v162, v163
	v_pk_mul_f32 v[166:167], v[74:75], v[66:67]
	v_cvt_pk_bf16_f32 v163, v164, v165
	v_pk_mul_f32 v[168:169], v[72:73], v[64:65]
	s_nop 0
	v_cvt_pk_bf16_f32 v164, v168, v169
	v_cvt_pk_bf16_f32 v165, v166, v167
	global_store_dwordx4 v[154:155], v[162:165], off sc1
	v_pk_mul_f32 v[154:155], v[62:63], v[54:55]
	v_pk_mul_f32 v[166:167], v[58:59], v[50:51]
	v_pk_mul_f32 v[162:163], v[60:61], v[52:53]
	v_pk_mul_f32 v[164:165], v[56:57], v[48:49]
	v_cvt_pk_bf16_f32 v162, v162, v163
	v_cvt_pk_bf16_f32 v163, v154, v155
	v_add_co_u32_e32 v154, vcc, s0, v152
	v_cvt_pk_bf16_f32 v164, v164, v165
	v_cvt_pk_bf16_f32 v165, v166, v167
	s_mov_b32 s0, 0x48000
	s_nop 0
	v_addc_co_u32_e32 v155, vcc, 0, v153, vcc
	global_store_dwordx4 v[154:155], v[162:165], off sc1
	v_pk_mul_f32 v[154:155], v[46:47], v[38:39]
	v_pk_mul_f32 v[166:167], v[42:43], v[34:35]
	v_pk_mul_f32 v[162:163], v[44:45], v[36:37]
	v_pk_mul_f32 v[164:165], v[40:41], v[32:33]
	v_cvt_pk_bf16_f32 v162, v162, v163
	v_cvt_pk_bf16_f32 v163, v154, v155
	v_add_co_u32_e32 v154, vcc, s0, v152
	v_cvt_pk_bf16_f32 v164, v164, v165
	v_cvt_pk_bf16_f32 v165, v166, v167
	s_mov_b32 s0, 0x50000
	s_nop 0
	v_addc_co_u32_e32 v155, vcc, 0, v153, vcc
	global_store_dwordx4 v[154:155], v[162:165], off sc1
	v_pk_mul_f32 v[154:155], v[30:31], v[22:23]
	v_pk_mul_f32 v[166:167], v[26:27], v[18:19]
	v_pk_mul_f32 v[162:163], v[28:29], v[20:21]
	v_pk_mul_f32 v[164:165], v[24:25], v[16:17]
	v_cvt_pk_bf16_f32 v162, v162, v163
	v_cvt_pk_bf16_f32 v163, v154, v155
	v_add_co_u32_e32 v154, vcc, s0, v152
	v_cvt_pk_bf16_f32 v164, v164, v165
	v_cvt_pk_bf16_f32 v165, v166, v167
	v_pk_mul_f32 v[166:167], v[10:11], v[2:3]
	s_nop 0
	v_addc_co_u32_e32 v155, vcc, 0, v153, vcc
	v_add_co_u32_e32 v152, vcc, 0x58000, v152
	global_store_dwordx4 v[154:155], v[162:165], off sc1
	s_nop 0
	v_addc_co_u32_e32 v153, vcc, 0, v153, vcc
	v_pk_mul_f32 v[162:163], v[12:13], v[4:5]
	v_pk_mul_f32 v[164:165], v[8:9], v[0:1]
	v_pk_mul_f32 v[154:155], v[14:15], v[6:7]
	v_cvt_pk_bf16_f32 v162, v162, v163
	s_nop 0
	v_cvt_pk_bf16_f32 v163, v154, v155
	v_cvt_pk_bf16_f32 v164, v164, v165
	v_cvt_pk_bf16_f32 v165, v166, v167
	global_store_dwordx4 v[152:153], v[162:165], off sc1
	s_cbranch_execnz .LBB0_190
